# left-over in-proj tiles: the 8 workgroups of one XCD take 8 consecutive tiles (shared weight/activation tiles stay in one L2)
# speedup vs baseline: 1.0026x; 1.0026x over previous
; #define LAS __attribute__((address_space(3)))
;     __device__ bool next(int i, Unit& u) const {
;         const long L = (long)i * G + c; if (L >= nwg) return false;
;         int wgid = (int)L; { const int q = nwg / NXCD, r = nwg % NXCD, xcd = wgid % NXCD, off = wgid / NXCD; wgid = (xcd < r ? xcd * (q + 1) : r * (q + 1) + (xcd - r) * q) + off; }
;         const int nig = WGM * nN, gid = wgid / nig, fm = gid * WGM, gsz = (nM - fm) < WGM ? (nM - fm) : WGM;
;         u.pm = fm + ((wgid % nig) % gsz); u.pn = (wgid % nig) / gsz; u.mode = 0; return true;
;     }
; template <class Epi, class Sched>
; __device__ __forceinline__ void gemm_phase(LAS unsigned char* lds, const Sched& S, const Epi& E, const int K, const int lda, const int ldb, const int tid) {
;     const int wid = __builtin_amdgcn_readfirstlane(tid >> 6), lane = tid & 63, wr = wid >> 2, wc = wid & 3, fr = lane & 15, fq = lane >> 4;
;     const int nt = K / BK;
;     unsigned voffA[2], voffB[2];
; #pragma unroll
;     for (int i = 0; i < 2; ++i) { int R, C; stage_rc(tid * 16 + i * 8192, R, C); const int Rb = (R & ~31) + perm32(R & 31);
;         voffA[i] = (unsigned)(R * lda + C) * 2u; voffB[i] = (unsigned)(Rb * ldb + C) * 2u; }
;     const size_t kstep = (size_t)(BK * 2);
;     const size_t hstepA = (size_t)HALF * lda * 2, hstepB = (size_t)HALF * ldb * 2;
;     const unsigned ldsw = (unsigned)wid * 1024u;
;     const int aoff = lds_byte(wr * 64 + fr, fq * 8), boff = lds_byte(wc * 32 + fr, fq * 8);
.Lz1_p1entry:
	s_cmpk_gt_i32 s82, 0x93f
	v_readfirstlane_b32 s24, v244
	s_cbranch_scc1 .LBB0_582
	v_lshlrev_b32_e32 v0, 4, v244
	s_waitcnt vmcnt(0)
	v_add_u32_e32 v2, 0x2000, v0
	v_ashrrev_i32_e32 v3, 31, v2
	v_lshrrev_b32_e32 v3, 22, v3
	v_add_u32_e32 v3, v2, v3
	v_ashrrev_i32_e32 v10, 10, v3
	v_mul_i32_i24_e32 v3, 0x400, v10
	v_sub_u32_e32 v2, v2, v3
	v_lshrrev_b32_e32 v3, 4, v2
	v_bitop3_b32 v2, v3, v2, 32 bitop3:0x6c
	v_ashrrev_i32_e32 v3, 31, v2
	v_readlane_b32 s14, v254, 46
	v_lshrrev_b32_e32 v3, 26, v3
	v_readlane_b32 s15, v254, 47
	v_add_u32_e32 v3, v2, v3
	v_lshlrev_b32_e32 v4, 3, v10
	s_mov_b32 s15, s91
	v_ashrrev_i32_e32 v11, 6, v3
	v_and_b32_e32 v4, -16, v4
	s_lshl_b64 s[0:1], s[14:15], 26
	v_readlane_b32 s6, v254, 20
	v_add_u32_e32 v4, v11, v4
	s_add_u32 s25, s6, s0
	v_and_b32_e32 v5, 3, v11
	s_mov_b32 s0, 0xfffe0
	v_lshrrev_b32_e32 v6, 2, v4
	v_lshlrev_b32_e32 v7, 1, v4
	v_and_b32_e32 v3, 0xc0, v3
	v_and_or_b32 v5, v4, s0, v5
	v_and_b32_e32 v6, 4, v6
	v_and_b32_e32 v7, 24, v7
	v_sub_u32_e32 v2, v2, v3
	v_or3_b32 v5, v5, v6, v7
	v_lshlrev_b32_e32 v6, 5, v10
	v_ashrrev_i16_sdwa v2, v236, sext(v2) dst_sel:DWORD dst_unused:UNUSED_PAD src0_sel:DWORD src1_sel:BYTE_0
	v_and_b32_e32 v6, 32, v6
	v_bfe_i32 v12, v2, 0, 16
	v_add_lshl_u32 v2, v6, v12, 1
	v_lshl_add_u32 v146, v5, 12, v2
	v_lshl_add_u32 v148, v4, 12, v2
	v_bfe_i32 v2, v244, 27, 1
	v_lshrrev_b32_e32 v2, 22, v2
	v_add_u32_e32 v2, v0, v2
	v_and_b32_e32 v2, 0xfffffc00, v2
	v_sub_u32_e32 v0, v0, v2
	v_lshrrev_b32_e32 v2, 4, v0
	v_ashrrev_i32_e32 v3, 31, v244
	v_bitop3_b32 v0, v2, v0, 32 bitop3:0x6c
	v_lshrrev_b32_e32 v3, 26, v3
	v_ashrrev_i32_e32 v2, 31, v0
	v_add_u32_e32 v3, v244, v3
	v_lshrrev_b32_e32 v2, 26, v2
	v_ashrrev_i32_e32 v14, 6, v3
	v_add_u32_e32 v2, v0, v2
	v_lshlrev_b32_e32 v3, 3, v14
	v_readlane_b32 s7, v254, 21
	v_ashrrev_i32_e32 v13, 6, v2
	v_and_b32_e32 v3, -16, v3
	s_addc_u32 s26, s7, s1
	v_add_u32_e32 v3, v13, v3
	v_and_b32_e32 v4, 3, v13
	s_ashr_i32 s28, s82, 31
	v_and_or_b32 v4, v3, s0, v4
	s_lshr_b32 s0, s28, 29
	s_add_i32 s0, s82, s0
	s_ashr_i32 s10, s24, 6
	s_ashr_i32 s1, s0, 3
	s_and_b32 s0, s0, -8
	s_ashr_i32 s7, s24, 8
	s_lshl_b32 s27, s10, 10
	s_sub_i32 s0, s82, s0
	s_cmp_lt_i32 s0, 0
	s_movk_i32 s6, 0x129
	s_cselect_b32 s6, s6, 0x128
	s_cmpk_eq_u32 s42, 0x100
	s_cselect_b32 s6, 0x120, s6
	s_mul_i32 s0, s6, s0
	s_add_i32 s0, s0, s1
	v_readlane_b32 s1, v255, 6
	s_cmp_eq_u32 s1, 0
	s_cbranch_scc1 .Lz1_nf
	s_and_b32 s0, s82, 7
	s_lshl_b32 s0, s0, 3
	s_lshr_b32 s1, s82, 3
	s_add_i32 s0, s0, s1
	s_addk_i32 s0, 0x900
